# row-scale LDS reads of the SwiGLU and projection epilogues issued together at the epilogue top
# speedup vs baseline: 1.0001x; 1.0001x over previous
.LBB0_631:
	v_lshl_add_u32 v145, s47, 10, v142
	ds_read2_b32 v[146:147], v145 offset1:16
	ds_read2_b32 v[212:213], v145 offset0:32 offset1:48
	ds_read2_b32 v[214:215], v145 offset0:128 offset1:144
	ds_read2_b32 v[216:217], v145 offset0:160 offset1:176
	v_lshl_or_b32 v148, s27, 8, v143
	v_lshl_add_u32 v152, s26, 8, v140
	v_ashrrev_i32_e32 v149, 31, v148
	s_andn2_b64 vcc, exec, s[34:35]
	s_waitcnt lgkmcnt(0)
	v_pk_mul_f32 v[128:129], v[128:129], v[146:147] op_sel_hi:[1,0]
	v_pk_mul_f32 v[126:127], v[126:127], v[146:147] op_sel_hi:[1,0]
	v_pk_mul_f32 v[122:123], v[122:123], v[146:147] op_sel_hi:[1,0]
	v_pk_mul_f32 v[124:125], v[124:125], v[146:147] op_sel_hi:[1,0]
	v_cvt_pk_bf16_f32 v126, v126, v127
	v_cvt_pk_bf16_f32 v127, v128, v129
	v_cvt_pk_bf16_f32 v128, v122, v123
	v_mov_b64_e32 v[122:123], s[10:11]
	v_cvt_pk_bf16_f32 v129, v124, v125
	v_mad_i64_i32 v[150:151], s[26:27], v152, s23, v[122:123]
	v_lshlrev_b64 v[124:125], 1, v[148:149]
	v_lshl_add_u64 v[148:149], v[150:151], 0, v[124:125]
	global_store_dwordx4 v[148:149], v[126:129], off sc0 sc1
	v_pk_mul_f32 v[116:117], v[116:117], v[146:147] op_sel_hi:[1,0]
	v_pk_mul_f32 v[114:115], v[114:115], v[146:147] op_sel_hi:[1,0]
	v_pk_mul_f32 v[126:127], v[108:109], v[146:147] op_sel_hi:[1,0]
	v_pk_mul_f32 v[108:109], v[106:107], v[146:147] op_sel_hi:[1,0]
	v_cvt_pk_bf16_f32 v106, v114, v115
	v_cvt_pk_bf16_f32 v107, v116, v117
	v_cvt_pk_bf16_f32 v108, v108, v109
	v_cvt_pk_bf16_f32 v109, v126, v127
	v_or_b32_e32 v115, 16, v152
	v_mov_b32_e32 v114, v147
	global_store_dwordx4 v[148:149], v[106:109], off offset:256 sc0 sc1
	v_pk_mul_f32 v[110:111], v[110:111], v[114:115] op_sel_hi:[1,0]
	v_pk_mul_f32 v[112:113], v[112:113], v[114:115] op_sel_hi:[1,0]
	v_pk_mul_f32 v[108:109], v[120:121], v[114:115] op_sel_hi:[1,0]
	v_pk_mul_f32 v[106:107], v[118:119], v[114:115] op_sel_hi:[1,0]
	v_pk_mul_f32 v[102:103], v[102:103], v[114:115] op_sel_hi:[1,0]
	v_cvt_pk_bf16_f32 v106, v106, v107
	v_cvt_pk_bf16_f32 v107, v108, v109
	v_cvt_pk_bf16_f32 v108, v110, v111
	v_mad_i64_i32 v[110:111], s[26:27], v115, s23, v[122:123]
	v_cvt_pk_bf16_f32 v109, v112, v113
	v_lshl_add_u64 v[110:111], v[110:111], 0, v[124:125]
	global_store_dwordx4 v[110:111], v[106:109], off sc0 sc1
	v_pk_mul_f32 v[104:105], v[104:105], v[114:115] op_sel_hi:[1,0]
	s_nop 0
	v_pk_mul_f32 v[106:107], v[96:97], v[114:115] op_sel_hi:[1,0]
	v_pk_mul_f32 v[96:97], v[94:95], v[114:115] op_sel_hi:[1,0]
	v_cvt_pk_bf16_f32 v94, v102, v103
	v_mov_b32_e32 v102, v212
	v_mov_b32_e32 v103, v213
	v_cvt_pk_bf16_f32 v95, v104, v105
	v_cvt_pk_bf16_f32 v96, v96, v97
	v_cvt_pk_bf16_f32 v97, v106, v107
	global_store_dwordx4 v[110:111], v[94:97], off offset:256 sc0 sc1
	v_or_b32_e32 v104, 32, v152
	s_waitcnt lgkmcnt(0)
	v_pk_mul_f32 v[84:85], v[84:85], v[102:103] op_sel_hi:[1,0]
	v_pk_mul_f32 v[94:95], v[100:101], v[102:103] op_sel_hi:[1,0]
	v_pk_mul_f32 v[96:97], v[98:99], v[102:103] op_sel_hi:[1,0]
	v_pk_mul_f32 v[98:99], v[92:93], v[102:103] op_sel_hi:[1,0]
	v_pk_mul_f32 v[92:93], v[90:91], v[102:103] op_sel_hi:[1,0]
	v_cvt_pk_bf16_f32 v91, v94, v95
	v_mad_i64_i32 v[94:95], s[26:27], v104, s23, v[122:123]
	v_cvt_pk_bf16_f32 v90, v96, v97
	v_cvt_pk_bf16_f32 v92, v92, v93
	v_cvt_pk_bf16_f32 v93, v98, v99
	v_lshl_add_u64 v[94:95], v[94:95], 0, v[124:125]
	global_store_dwordx4 v[94:95], v[90:93], off sc0 sc1
	v_pk_mul_f32 v[82:83], v[82:83], v[102:103] op_sel_hi:[1,0]
	s_nop 0
	v_pk_mul_f32 v[90:91], v[76:77], v[102:103] op_sel_hi:[1,0]
	v_pk_mul_f32 v[76:77], v[74:75], v[102:103] op_sel_hi:[1,0]
	v_cvt_pk_bf16_f32 v74, v82, v83
	v_cvt_pk_bf16_f32 v75, v84, v85
	v_cvt_pk_bf16_f32 v76, v76, v77
	v_cvt_pk_bf16_f32 v77, v90, v91
	v_or_b32_e32 v83, 48, v152
	v_mov_b32_e32 v82, v103
	global_store_dwordx4 v[94:95], v[74:77], off offset:256 sc0 sc1
	v_pk_mul_f32 v[78:79], v[78:79], v[82:83] op_sel_hi:[1,0]
	v_pk_mul_f32 v[80:81], v[80:81], v[82:83] op_sel_hi:[1,0]
	v_pk_mul_f32 v[76:77], v[88:89], v[82:83] op_sel_hi:[1,0]
	v_pk_mul_f32 v[74:75], v[86:87], v[82:83] op_sel_hi:[1,0]
	v_pk_mul_f32 v[70:71], v[70:71], v[82:83] op_sel_hi:[1,0]
	v_cvt_pk_bf16_f32 v74, v74, v75
	v_cvt_pk_bf16_f32 v75, v76, v77
	v_cvt_pk_bf16_f32 v76, v78, v79
	v_mad_i64_i32 v[78:79], s[26:27], v83, s23, v[122:123]
	v_cvt_pk_bf16_f32 v77, v80, v81
	v_lshl_add_u64 v[78:79], v[78:79], 0, v[124:125]
	global_store_dwordx4 v[78:79], v[74:77], off sc0 sc1
	v_pk_mul_f32 v[72:73], v[72:73], v[82:83] op_sel_hi:[1,0]
	s_nop 0
	v_pk_mul_f32 v[74:75], v[68:69], v[82:83] op_sel_hi:[1,0]
	v_pk_mul_f32 v[68:69], v[66:67], v[82:83] op_sel_hi:[1,0]
	v_cvt_pk_bf16_f32 v66, v70, v71
	v_mov_b32_e32 v70, v214
	v_mov_b32_e32 v71, v215
	v_cvt_pk_bf16_f32 v67, v72, v73
	v_cvt_pk_bf16_f32 v68, v68, v69
	v_cvt_pk_bf16_f32 v69, v74, v75
	global_store_dwordx4 v[78:79], v[66:69], off offset:256 sc0 sc1
	s_waitcnt lgkmcnt(0)
	v_pk_mul_f32 v[62:63], v[62:63], v[70:71] op_sel_hi:[1,0]
	v_pk_mul_f32 v[64:65], v[64:65], v[70:71] op_sel_hi:[1,0]
	v_add_u32_e32 v68, 0x80, v152
	v_pk_mul_f32 v[66:67], v[60:61], v[70:71] op_sel_hi:[1,0]
	v_pk_mul_f32 v[60:61], v[58:59], v[70:71] op_sel_hi:[1,0]
	v_cvt_pk_bf16_f32 v58, v62, v63
	v_mad_i64_i32 v[62:63], s[26:27], v68, s23, v[122:123]
	v_cvt_pk_bf16_f32 v59, v64, v65
	v_cvt_pk_bf16_f32 v60, v60, v61
	v_cvt_pk_bf16_f32 v61, v66, v67
	v_lshl_add_u64 v[62:63], v[62:63], 0, v[124:125]
	global_store_dwordx4 v[62:63], v[58:61], off sc0 sc1
	v_pk_mul_f32 v[52:53], v[52:53], v[70:71] op_sel_hi:[1,0]
	v_pk_mul_f32 v[50:51], v[50:51], v[70:71] op_sel_hi:[1,0]
	v_pk_mul_f32 v[58:59], v[44:45], v[70:71] op_sel_hi:[1,0]
	v_pk_mul_f32 v[44:45], v[42:43], v[70:71] op_sel_hi:[1,0]
	v_cvt_pk_bf16_f32 v42, v50, v51
	v_cvt_pk_bf16_f32 v43, v52, v53
	v_cvt_pk_bf16_f32 v44, v44, v45
	v_cvt_pk_bf16_f32 v45, v58, v59
	v_add_u32_e32 v51, 0x90, v152
	v_mov_b32_e32 v50, v71
	global_store_dwordx4 v[62:63], v[42:45], off offset:256 sc0 sc1
	v_pk_mul_f32 v[46:47], v[46:47], v[50:51] op_sel_hi:[1,0]
	v_pk_mul_f32 v[48:49], v[48:49], v[50:51] op_sel_hi:[1,0]
	v_pk_mul_f32 v[44:45], v[56:57], v[50:51] op_sel_hi:[1,0]
	v_pk_mul_f32 v[42:43], v[54:55], v[50:51] op_sel_hi:[1,0]
	v_pk_mul_f32 v[38:39], v[38:39], v[50:51] op_sel_hi:[1,0]
	v_cvt_pk_bf16_f32 v42, v42, v43
	v_cvt_pk_bf16_f32 v43, v44, v45
	v_cvt_pk_bf16_f32 v44, v46, v47
	v_mad_i64_i32 v[46:47], s[26:27], v51, s23, v[122:123]
	v_cvt_pk_bf16_f32 v45, v48, v49
	v_lshl_add_u64 v[46:47], v[46:47], 0, v[124:125]
	global_store_dwordx4 v[46:47], v[42:45], off sc0 sc1
	v_pk_mul_f32 v[40:41], v[40:41], v[50:51] op_sel_hi:[1,0]
	s_nop 0
	v_pk_mul_f32 v[42:43], v[32:33], v[50:51] op_sel_hi:[1,0]
	v_pk_mul_f32 v[32:33], v[30:31], v[50:51] op_sel_hi:[1,0]
	v_cvt_pk_bf16_f32 v30, v38, v39
	v_mov_b32_e32 v38, v216
	v_mov_b32_e32 v39, v217
	v_cvt_pk_bf16_f32 v31, v40, v41
	v_cvt_pk_bf16_f32 v32, v32, v33
	v_cvt_pk_bf16_f32 v33, v42, v43
	global_store_dwordx4 v[46:47], v[30:33], off offset:256 sc0 sc1
	v_add_u32_e32 v40, 0xa0, v152
	s_waitcnt lgkmcnt(0)
	v_pk_mul_f32 v[20:21], v[20:21], v[38:39] op_sel_hi:[1,0]
	v_pk_mul_f32 v[30:31], v[36:37], v[38:39] op_sel_hi:[1,0]
	v_pk_mul_f32 v[32:33], v[34:35], v[38:39] op_sel_hi:[1,0]
	v_pk_mul_f32 v[34:35], v[28:29], v[38:39] op_sel_hi:[1,0]
	v_pk_mul_f32 v[28:29], v[26:27], v[38:39] op_sel_hi:[1,0]
	v_cvt_pk_bf16_f32 v27, v30, v31
	v_mad_i64_i32 v[30:31], s[26:27], v40, s23, v[122:123]
	v_cvt_pk_bf16_f32 v26, v32, v33
	v_cvt_pk_bf16_f32 v28, v28, v29
	v_cvt_pk_bf16_f32 v29, v34, v35
	v_lshl_add_u64 v[30:31], v[30:31], 0, v[124:125]
	global_store_dwordx4 v[30:31], v[26:29], off sc0 sc1
	v_pk_mul_f32 v[18:19], v[18:19], v[38:39] op_sel_hi:[1,0]
	s_nop 0
	v_pk_mul_f32 v[26:27], v[12:13], v[38:39] op_sel_hi:[1,0]
	v_pk_mul_f32 v[12:13], v[10:11], v[38:39] op_sel_hi:[1,0]
	v_cvt_pk_bf16_f32 v10, v18, v19
	v_cvt_pk_bf16_f32 v11, v20, v21
	v_cvt_pk_bf16_f32 v12, v12, v13
	v_cvt_pk_bf16_f32 v13, v26, v27
	v_add_u32_e32 v19, 0xb0, v152
	v_mov_b32_e32 v18, v39
	global_store_dwordx4 v[30:31], v[10:13], off offset:256 sc0 sc1
	v_pk_mul_f32 v[14:15], v[14:15], v[18:19] op_sel_hi:[1,0]
	v_pk_mul_f32 v[16:17], v[16:17], v[18:19] op_sel_hi:[1,0]
	v_pk_mul_f32 v[12:13], v[24:25], v[18:19] op_sel_hi:[1,0]
	v_pk_mul_f32 v[10:11], v[22:23], v[18:19] op_sel_hi:[1,0]
	v_pk_mul_f32 v[8:9], v[8:9], v[18:19] op_sel_hi:[1,0]
	v_cvt_pk_bf16_f32 v10, v10, v11
	v_cvt_pk_bf16_f32 v11, v12, v13
	v_cvt_pk_bf16_f32 v12, v14, v15
	v_mad_i64_i32 v[14:15], s[26:27], v19, s23, v[122:123]
	v_cvt_pk_bf16_f32 v13, v16, v17
	v_lshl_add_u64 v[14:15], v[14:15], 0, v[124:125]
	global_store_dwordx4 v[14:15], v[10:13], off sc0 sc1
	v_pk_mul_f32 v[6:7], v[6:7], v[18:19] op_sel_hi:[1,0]
	s_mov_b64 s[26:27], -1
	v_pk_mul_f32 v[10:11], v[4:5], v[18:19] op_sel_hi:[1,0]
	v_pk_mul_f32 v[4:5], v[2:3], v[18:19] op_sel_hi:[1,0]
	v_cvt_pk_bf16_f32 v2, v6, v7
	v_cvt_pk_bf16_f32 v3, v8, v9
	v_cvt_pk_bf16_f32 v4, v4, v5
	v_cvt_pk_bf16_f32 v5, v10, v11
	global_store_dwordx4 v[14:15], v[2:5], off offset:256 sc0 sc1
	s_cbranch_vccnz .LBB0_624
	s_andn2_b64 vcc, exec, s[2:3]
	s_cbranch_vccnz .LBB0_623
	s_barrier
	s_branch .LBB0_623

.LBB0_815:
	v_mov_b32_e32 v244, 0xbfb8aa3b
	v_mov_b32_e32 v245, 0xbfb8aa3b
	v_mov_b32_e32 v246, 1.0
	v_mov_b32_e32 v247, 1.0
	v_lshl_add_u32 v150, s49, 10, v146
	ds_read2_b32 v[142:143], v150 offset1:16
	ds_read2_b32 v[212:213], v150 offset0:32 offset1:48
	ds_read2_b32 v[214:215], v150 offset0:128 offset1:144
	ds_read2_b32 v[216:217], v150 offset0:160 offset1:176
	v_lshl_or_b32 v140, s31, 7, v147
	v_lshl_add_u32 v149, s30, 8, v144
	v_ashrrev_i32_e32 v141, 31, v140
	s_movk_i32 s15, 0x1600
	s_waitcnt lgkmcnt(0)
	v_pk_mul_f32 v[126:127], v[126:127], v[142:143] op_sel_hi:[1,0]
	v_pk_mul_f32 v[122:123], v[122:123], v[142:143] op_sel_hi:[1,0]
	v_mul_f32_e32 v151, 0xbfb8aa3b, v126
	v_exp_f32_e32 v151, v151
	v_pk_mul_f32 v[124:125], v[124:125], v[142:143] op_sel_hi:[1,0]
	v_pk_mul_f32 v[118:119], v[118:119], v[142:143] op_sel_hi:[1,0]
	v_pk_mul_f32 v[114:115], v[114:115], v[142:143] op_sel_hi:[1,0]
	v_add_f32_e32 v151, 1.0, v151
	v_rcp_f32_e32 v152, v151
	v_mul_f32_e32 v151, 0xbfb8aa3b, v127
	v_exp_f32_e32 v151, v151
	v_pk_mul_f32 v[116:117], v[116:117], v[142:143] op_sel_hi:[1,0]
	s_andn2_b64 vcc, exec, s[34:35]
	v_add_f32_e32 v151, 1.0, v151
	v_rcp_f32_e32 v153, v151
	s_nop 0
	v_pk_mul_f32 v[126:127], v[126:127], v[152:153]
	s_nop 0
	v_pk_mul_f32 v[122:123], v[122:123], v[126:127]
	v_pk_mul_f32 v[126:127], v[128:129], v[142:143] op_sel_hi:[1,0]
	s_nop 0
	v_pk_mul_f32 v[128:129], v[126:127], v[244:245]
	v_exp_f32_e32 v128, v128
	v_exp_f32_e32 v129, v129
	s_nop 0
	v_pk_add_f32 v[128:129], v[128:129], v[246:247]
	v_rcp_f32_e32 v128, v128
	v_rcp_f32_e32 v129, v129
	s_nop 0
	v_pk_mul_f32 v[126:127], v[126:127], v[128:129]
	s_nop 0
	v_pk_mul_f32 v[124:125], v[124:125], v[126:127]
	v_pk_mul_f32 v[126:127], v[118:119], v[244:245]
	v_exp_f32_e32 v126, v126
	v_exp_f32_e32 v127, v127
	s_nop 0
	v_pk_add_f32 v[126:127], v[126:127], v[246:247]
	v_rcp_f32_e32 v126, v126
	v_rcp_f32_e32 v127, v127
	s_nop 0
	v_pk_mul_f32 v[118:119], v[118:119], v[126:127]
	s_nop 0
	v_pk_mul_f32 v[114:115], v[114:115], v[118:119]
	v_pk_mul_f32 v[118:119], v[120:121], v[142:143] op_sel_hi:[1,0]
	s_nop 0
	v_pk_mul_f32 v[120:121], v[118:119], v[244:245]
	v_exp_f32_e32 v120, v120
	v_exp_f32_e32 v121, v121
	s_nop 0
	v_pk_add_f32 v[120:121], v[120:121], v[246:247]
	v_rcp_f32_e32 v120, v120
	v_rcp_f32_e32 v121, v121
	s_nop 0
	v_pk_mul_f32 v[118:119], v[118:119], v[120:121]
	s_nop 0
	v_pk_mul_f32 v[116:117], v[116:117], v[118:119]
	v_cvt_pk_bf16_f32 v120, v114, v115
	v_mov_b64_e32 v[114:115], s[10:11]
	v_cvt_pk_bf16_f32 v118, v122, v123
	v_cvt_pk_bf16_f32 v121, v116, v117
	v_mad_i64_i32 v[122:123], s[30:31], v149, s15, v[114:115]
	v_lshlrev_b64 v[116:117], 1, v[140:141]
	v_cvt_pk_bf16_f32 v119, v124, v125
	v_lshl_add_u64 v[122:123], v[122:123], 0, v[116:117]
	global_store_dwordx4 v[122:123], v[118:121], off sc0 sc1
	s_nop 1
	v_mov_b32_e32 v118, v143
	v_pk_mul_f32 v[110:111], v[110:111], v[118:119] op_sel_hi:[1,0]
	s_nop 0
	v_mul_f32_e32 v119, 0xbfb8aa3b, v110
	v_exp_f32_e32 v119, v119
	s_nop 0
	v_add_f32_e32 v119, 1.0, v119
	v_rcp_f32_e32 v120, v119
	v_pk_mul_f32 v[106:107], v[106:107], v[118:119] op_sel_hi:[1,0]
	v_mul_f32_e32 v119, 0xbfb8aa3b, v111
	v_exp_f32_e32 v119, v119
	s_nop 0
	v_add_f32_e32 v119, 1.0, v119
	v_rcp_f32_e32 v121, v119
	v_pk_mul_f32 v[108:109], v[108:109], v[118:119] op_sel_hi:[1,0]
	v_pk_mul_f32 v[102:103], v[102:103], v[118:119] op_sel_hi:[1,0]
	v_pk_mul_f32 v[98:99], v[98:99], v[118:119] op_sel_hi:[1,0]
	v_pk_mul_f32 v[110:111], v[110:111], v[120:121]
	v_pk_mul_f32 v[100:101], v[100:101], v[118:119] op_sel_hi:[1,0]
	v_pk_mul_f32 v[106:107], v[106:107], v[110:111]
	v_pk_mul_f32 v[110:111], v[112:113], v[118:119] op_sel_hi:[1,0]
	s_nop 0
	v_pk_mul_f32 v[112:113], v[110:111], v[244:245]
	v_exp_f32_e32 v112, v112
	v_exp_f32_e32 v113, v113
	s_nop 0
	v_pk_add_f32 v[112:113], v[112:113], v[246:247]
	v_rcp_f32_e32 v112, v112
	v_rcp_f32_e32 v113, v113
	s_nop 0
	v_pk_mul_f32 v[110:111], v[110:111], v[112:113]
	s_nop 0
	v_pk_mul_f32 v[108:109], v[108:109], v[110:111]
	v_pk_mul_f32 v[110:111], v[102:103], v[244:245]
	v_exp_f32_e32 v110, v110
	v_exp_f32_e32 v111, v111
	s_nop 0
	v_pk_add_f32 v[110:111], v[110:111], v[246:247]
	v_rcp_f32_e32 v110, v110
	v_rcp_f32_e32 v111, v111
	s_nop 0
	v_pk_mul_f32 v[102:103], v[102:103], v[110:111]
	s_nop 0
	v_pk_mul_f32 v[102:103], v[98:99], v[102:103]
	v_pk_mul_f32 v[98:99], v[104:105], v[118:119] op_sel_hi:[1,0]
	v_or_b32_e32 v110, 16, v149
	v_pk_mul_f32 v[104:105], v[98:99], v[244:245]
	v_exp_f32_e32 v104, v104
	v_exp_f32_e32 v105, v105
	s_nop 0
	v_pk_add_f32 v[104:105], v[104:105], v[246:247]
	v_rcp_f32_e32 v104, v104
	v_rcp_f32_e32 v105, v105
	s_nop 0
	v_pk_mul_f32 v[98:99], v[98:99], v[104:105]
	s_nop 0
	v_pk_mul_f32 v[104:105], v[100:101], v[98:99]
	v_cvt_pk_bf16_f32 v100, v102, v103
	v_mad_i64_i32 v[102:103], s[30:31], v110, s15, v[114:115]
	v_cvt_pk_bf16_f32 v98, v106, v107
	v_cvt_pk_bf16_f32 v99, v108, v109
	v_cvt_pk_bf16_f32 v101, v104, v105
	v_lshl_add_u64 v[102:103], v[102:103], 0, v[116:117]
	global_store_dwordx4 v[102:103], v[98:101], off sc0 sc1
	s_nop 1
	v_mov_b32_e32 v98, v212
	v_mov_b32_e32 v99, v213
	s_waitcnt lgkmcnt(0)
	v_pk_mul_f32 v[94:95], v[94:95], v[98:99] op_sel_hi:[1,0]
	s_nop 0
	v_pk_mul_f32 v[100:101], v[94:95], v[244:245]
	v_exp_f32_e32 v100, v100
	v_exp_f32_e32 v101, v101
	v_pk_mul_f32 v[90:91], v[90:91], v[98:99] op_sel_hi:[1,0]
	v_pk_mul_f32 v[92:93], v[92:93], v[98:99] op_sel_hi:[1,0]
	v_pk_add_f32 v[100:101], v[100:101], v[246:247]
	v_rcp_f32_e32 v100, v100
	v_rcp_f32_e32 v101, v101
	v_pk_mul_f32 v[86:87], v[86:87], v[98:99] op_sel_hi:[1,0]
	v_pk_mul_f32 v[82:83], v[82:83], v[98:99] op_sel_hi:[1,0]
	v_pk_mul_f32 v[84:85], v[84:85], v[98:99] op_sel_hi:[1,0]
	v_pk_mul_f32 v[94:95], v[94:95], v[100:101]
	s_nop 0
	v_pk_mul_f32 v[90:91], v[90:91], v[94:95]
	v_pk_mul_f32 v[94:95], v[96:97], v[98:99] op_sel_hi:[1,0]
	s_nop 0
	v_pk_mul_f32 v[96:97], v[94:95], v[244:245]
	v_exp_f32_e32 v96, v96
	v_exp_f32_e32 v97, v97
	s_nop 0
	v_pk_add_f32 v[96:97], v[96:97], v[246:247]
	v_rcp_f32_e32 v96, v96
	v_rcp_f32_e32 v97, v97
	s_nop 0
	v_pk_mul_f32 v[94:95], v[94:95], v[96:97]
	s_nop 0
	v_pk_mul_f32 v[92:93], v[92:93], v[94:95]
	v_pk_mul_f32 v[94:95], v[86:87], v[244:245]
	v_exp_f32_e32 v94, v94
	v_exp_f32_e32 v95, v95
	s_nop 0
	v_pk_add_f32 v[94:95], v[94:95], v[246:247]
	v_rcp_f32_e32 v94, v94
	v_rcp_f32_e32 v95, v95
	s_nop 0
	v_pk_mul_f32 v[86:87], v[86:87], v[94:95]
	s_nop 0
	v_pk_mul_f32 v[86:87], v[82:83], v[86:87]
	v_pk_mul_f32 v[82:83], v[88:89], v[98:99] op_sel_hi:[1,0]
	v_or_b32_e32 v94, 32, v149
	v_pk_mul_f32 v[88:89], v[82:83], v[244:245]
	v_exp_f32_e32 v88, v88
	v_exp_f32_e32 v89, v89
	s_nop 0
	v_pk_add_f32 v[88:89], v[88:89], v[246:247]
	v_rcp_f32_e32 v88, v88
	v_rcp_f32_e32 v89, v89
	s_nop 0
	v_pk_mul_f32 v[82:83], v[82:83], v[88:89]
	s_nop 0
	v_pk_mul_f32 v[88:89], v[84:85], v[82:83]
	v_cvt_pk_bf16_f32 v84, v86, v87
	v_mad_i64_i32 v[86:87], s[30:31], v94, s15, v[114:115]
	v_cvt_pk_bf16_f32 v82, v90, v91
	v_cvt_pk_bf16_f32 v83, v92, v93
	v_cvt_pk_bf16_f32 v85, v88, v89
	v_lshl_add_u64 v[86:87], v[86:87], 0, v[116:117]
	global_store_dwordx4 v[86:87], v[82:85], off sc0 sc1
	s_nop 1
	v_mov_b32_e32 v82, v99
	v_pk_mul_f32 v[78:79], v[78:79], v[82:83] op_sel_hi:[1,0]
	s_nop 0
	v_mul_f32_e32 v83, 0xbfb8aa3b, v78
	v_exp_f32_e32 v83, v83
	s_nop 0
	v_add_f32_e32 v83, 1.0, v83
	v_rcp_f32_e32 v84, v83
	v_pk_mul_f32 v[74:75], v[74:75], v[82:83] op_sel_hi:[1,0]
	v_mul_f32_e32 v83, 0xbfb8aa3b, v79
	v_exp_f32_e32 v83, v83
	s_nop 0
	v_add_f32_e32 v83, 1.0, v83
	v_rcp_f32_e32 v85, v83
	v_pk_mul_f32 v[76:77], v[76:77], v[82:83] op_sel_hi:[1,0]
	v_pk_mul_f32 v[70:71], v[70:71], v[82:83] op_sel_hi:[1,0]
	v_pk_mul_f32 v[66:67], v[66:67], v[82:83] op_sel_hi:[1,0]
	v_pk_mul_f32 v[78:79], v[78:79], v[84:85]
	v_pk_mul_f32 v[68:69], v[68:69], v[82:83] op_sel_hi:[1,0]
	v_pk_mul_f32 v[74:75], v[74:75], v[78:79]
	v_pk_mul_f32 v[78:79], v[80:81], v[82:83] op_sel_hi:[1,0]
	s_nop 0
	v_pk_mul_f32 v[80:81], v[78:79], v[244:245]
	v_exp_f32_e32 v80, v80
	v_exp_f32_e32 v81, v81
	s_nop 0
	v_pk_add_f32 v[80:81], v[80:81], v[246:247]
	v_rcp_f32_e32 v80, v80
	v_rcp_f32_e32 v81, v81
	s_nop 0
	v_pk_mul_f32 v[78:79], v[78:79], v[80:81]
	s_nop 0
	v_pk_mul_f32 v[76:77], v[76:77], v[78:79]
	v_pk_mul_f32 v[78:79], v[70:71], v[244:245]
	v_exp_f32_e32 v78, v78
	v_exp_f32_e32 v79, v79
	s_nop 0
	v_pk_add_f32 v[78:79], v[78:79], v[246:247]
	v_rcp_f32_e32 v78, v78
	v_rcp_f32_e32 v79, v79
	s_nop 0
	v_pk_mul_f32 v[70:71], v[70:71], v[78:79]
	s_nop 0
	v_pk_mul_f32 v[70:71], v[66:67], v[70:71]
	v_pk_mul_f32 v[66:67], v[72:73], v[82:83] op_sel_hi:[1,0]
	v_or_b32_e32 v78, 48, v149
	v_pk_mul_f32 v[72:73], v[66:67], v[244:245]
	v_exp_f32_e32 v72, v72
	v_exp_f32_e32 v73, v73
	s_nop 0
	v_pk_add_f32 v[72:73], v[72:73], v[246:247]
	v_rcp_f32_e32 v72, v72
	v_rcp_f32_e32 v73, v73
	s_nop 0
	v_pk_mul_f32 v[66:67], v[66:67], v[72:73]
	s_nop 0
	v_pk_mul_f32 v[72:73], v[68:69], v[66:67]
	v_cvt_pk_bf16_f32 v68, v70, v71
	v_mad_i64_i32 v[70:71], s[30:31], v78, s15, v[114:115]
	v_cvt_pk_bf16_f32 v66, v74, v75
	v_cvt_pk_bf16_f32 v67, v76, v77
	v_cvt_pk_bf16_f32 v69, v72, v73
	v_lshl_add_u64 v[70:71], v[70:71], 0, v[116:117]
	global_store_dwordx4 v[70:71], v[66:69], off sc0 sc1
	s_nop 1
	v_mov_b32_e32 v66, v214
	v_mov_b32_e32 v67, v215
	v_add_u32_e32 v70, 0x80, v149
	s_waitcnt lgkmcnt(0)
	v_pk_mul_f32 v[62:63], v[62:63], v[66:67] op_sel_hi:[1,0]
	s_nop 0
	v_pk_mul_f32 v[68:69], v[62:63], v[244:245]
	v_exp_f32_e32 v68, v68
	v_exp_f32_e32 v69, v69
	v_pk_mul_f32 v[58:59], v[58:59], v[66:67] op_sel_hi:[1,0]
	v_pk_mul_f32 v[60:61], v[60:61], v[66:67] op_sel_hi:[1,0]
	v_pk_add_f32 v[68:69], v[68:69], v[246:247]
	v_rcp_f32_e32 v68, v68
	v_rcp_f32_e32 v69, v69
	v_pk_mul_f32 v[54:55], v[54:55], v[66:67] op_sel_hi:[1,0]
	v_pk_mul_f32 v[50:51], v[50:51], v[66:67] op_sel_hi:[1,0]
	v_pk_mul_f32 v[52:53], v[52:53], v[66:67] op_sel_hi:[1,0]
	v_pk_mul_f32 v[62:63], v[62:63], v[68:69]
	s_nop 0
	v_pk_mul_f32 v[58:59], v[58:59], v[62:63]
	v_pk_mul_f32 v[62:63], v[64:65], v[66:67] op_sel_hi:[1,0]
	s_nop 0
	v_pk_mul_f32 v[64:65], v[62:63], v[244:245]
	v_exp_f32_e32 v64, v64
	v_exp_f32_e32 v65, v65
	s_nop 0
	v_pk_add_f32 v[64:65], v[64:65], v[246:247]
	v_rcp_f32_e32 v64, v64
	v_rcp_f32_e32 v65, v65
	s_nop 0
	v_pk_mul_f32 v[62:63], v[62:63], v[64:65]
	s_nop 0
	v_pk_mul_f32 v[60:61], v[60:61], v[62:63]
	v_pk_mul_f32 v[62:63], v[54:55], v[244:245]
	v_exp_f32_e32 v62, v62
	v_exp_f32_e32 v63, v63
	s_nop 0
	v_pk_add_f32 v[62:63], v[62:63], v[246:247]
	v_rcp_f32_e32 v62, v62
	v_rcp_f32_e32 v63, v63
	s_nop 0
	v_pk_mul_f32 v[54:55], v[54:55], v[62:63]
	s_nop 0
	v_pk_mul_f32 v[54:55], v[50:51], v[54:55]
	v_pk_mul_f32 v[50:51], v[56:57], v[66:67] op_sel_hi:[1,0]
	s_nop 0
	v_pk_mul_f32 v[56:57], v[50:51], v[244:245]
	v_exp_f32_e32 v56, v56
	v_exp_f32_e32 v57, v57
	s_nop 0
	v_pk_add_f32 v[56:57], v[56:57], v[246:247]
	v_rcp_f32_e32 v56, v56
	v_rcp_f32_e32 v57, v57
	s_nop 0
	v_pk_mul_f32 v[50:51], v[50:51], v[56:57]
	s_nop 0
	v_pk_mul_f32 v[56:57], v[52:53], v[50:51]
	v_cvt_pk_bf16_f32 v52, v54, v55
	v_mad_i64_i32 v[54:55], s[30:31], v70, s15, v[114:115]
	v_cvt_pk_bf16_f32 v50, v58, v59
	v_cvt_pk_bf16_f32 v51, v60, v61
	v_cvt_pk_bf16_f32 v53, v56, v57
	v_lshl_add_u64 v[54:55], v[54:55], 0, v[116:117]
	global_store_dwordx4 v[54:55], v[50:53], off sc0 sc1
	s_nop 1
	v_mov_b32_e32 v50, v67
	v_pk_mul_f32 v[46:47], v[46:47], v[50:51] op_sel_hi:[1,0]
	s_nop 0
	v_mul_f32_e32 v51, 0xbfb8aa3b, v46
	v_exp_f32_e32 v51, v51
	s_nop 0
	v_add_f32_e32 v51, 1.0, v51
	v_rcp_f32_e32 v52, v51
	v_pk_mul_f32 v[42:43], v[42:43], v[50:51] op_sel_hi:[1,0]
	v_mul_f32_e32 v51, 0xbfb8aa3b, v47
	v_exp_f32_e32 v51, v51
	s_nop 0
	v_add_f32_e32 v51, 1.0, v51
	v_rcp_f32_e32 v53, v51
	v_pk_mul_f32 v[44:45], v[44:45], v[50:51] op_sel_hi:[1,0]
	v_pk_mul_f32 v[38:39], v[38:39], v[50:51] op_sel_hi:[1,0]
	v_pk_mul_f32 v[34:35], v[34:35], v[50:51] op_sel_hi:[1,0]
	v_pk_mul_f32 v[46:47], v[46:47], v[52:53]
	v_pk_mul_f32 v[36:37], v[36:37], v[50:51] op_sel_hi:[1,0]
	v_pk_mul_f32 v[42:43], v[42:43], v[46:47]
	v_pk_mul_f32 v[46:47], v[48:49], v[50:51] op_sel_hi:[1,0]
	s_nop 0
	v_pk_mul_f32 v[48:49], v[46:47], v[244:245]
	v_exp_f32_e32 v48, v48
	v_exp_f32_e32 v49, v49
	s_nop 0
	v_pk_add_f32 v[48:49], v[48:49], v[246:247]
	v_rcp_f32_e32 v48, v48
	v_rcp_f32_e32 v49, v49
	s_nop 0
	v_pk_mul_f32 v[46:47], v[46:47], v[48:49]
	s_nop 0
	v_pk_mul_f32 v[44:45], v[44:45], v[46:47]
	v_pk_mul_f32 v[46:47], v[38:39], v[244:245]
	v_exp_f32_e32 v46, v46
	v_exp_f32_e32 v47, v47
	s_nop 0
	v_pk_add_f32 v[46:47], v[46:47], v[246:247]
	v_rcp_f32_e32 v46, v46
	v_rcp_f32_e32 v47, v47
	s_nop 0
	v_pk_mul_f32 v[38:39], v[38:39], v[46:47]
	s_nop 0
	v_pk_mul_f32 v[38:39], v[34:35], v[38:39]
	v_pk_mul_f32 v[34:35], v[40:41], v[50:51] op_sel_hi:[1,0]
	v_add_u32_e32 v46, 0x90, v149
	v_pk_mul_f32 v[40:41], v[34:35], v[244:245]
	v_exp_f32_e32 v40, v40
	v_exp_f32_e32 v41, v41
	s_nop 0
	v_pk_add_f32 v[40:41], v[40:41], v[246:247]
	v_rcp_f32_e32 v40, v40
	v_rcp_f32_e32 v41, v41
	s_nop 0
	v_pk_mul_f32 v[34:35], v[34:35], v[40:41]
	s_nop 0
	v_pk_mul_f32 v[40:41], v[36:37], v[34:35]
	v_cvt_pk_bf16_f32 v36, v38, v39
	v_mad_i64_i32 v[38:39], s[30:31], v46, s15, v[114:115]
	v_cvt_pk_bf16_f32 v34, v42, v43
	v_cvt_pk_bf16_f32 v35, v44, v45
	v_cvt_pk_bf16_f32 v37, v40, v41
	v_lshl_add_u64 v[38:39], v[38:39], 0, v[116:117]
	global_store_dwordx4 v[38:39], v[34:37], off sc0 sc1
	s_nop 1
	v_mov_b32_e32 v34, v216
	v_mov_b32_e32 v35, v217
	s_waitcnt lgkmcnt(0)
	v_pk_mul_f32 v[30:31], v[30:31], v[34:35] op_sel_hi:[1,0]
	s_nop 0
	v_pk_mul_f32 v[36:37], v[30:31], v[244:245]
	v_exp_f32_e32 v36, v36
	v_exp_f32_e32 v37, v37
	v_pk_mul_f32 v[26:27], v[26:27], v[34:35] op_sel_hi:[1,0]
	v_pk_mul_f32 v[28:29], v[28:29], v[34:35] op_sel_hi:[1,0]
	v_pk_add_f32 v[36:37], v[36:37], v[246:247]
	v_rcp_f32_e32 v36, v36
	v_rcp_f32_e32 v37, v37
	v_pk_mul_f32 v[22:23], v[22:23], v[34:35] op_sel_hi:[1,0]
	v_pk_mul_f32 v[18:19], v[18:19], v[34:35] op_sel_hi:[1,0]
	v_pk_mul_f32 v[20:21], v[20:21], v[34:35] op_sel_hi:[1,0]
	v_pk_mul_f32 v[30:31], v[30:31], v[36:37]
	s_nop 0
	v_pk_mul_f32 v[26:27], v[26:27], v[30:31]
	v_pk_mul_f32 v[30:31], v[32:33], v[34:35] op_sel_hi:[1,0]
	s_nop 0
	v_pk_mul_f32 v[32:33], v[30:31], v[244:245]
	v_exp_f32_e32 v32, v32
	v_exp_f32_e32 v33, v33
	s_nop 0
	v_pk_add_f32 v[32:33], v[32:33], v[246:247]
	v_rcp_f32_e32 v32, v32
	v_rcp_f32_e32 v33, v33
	s_nop 0
	v_pk_mul_f32 v[30:31], v[30:31], v[32:33]
	s_nop 0
	v_pk_mul_f32 v[28:29], v[28:29], v[30:31]
	v_pk_mul_f32 v[30:31], v[22:23], v[244:245]
	v_exp_f32_e32 v30, v30
	v_exp_f32_e32 v31, v31
	s_nop 0
	v_pk_add_f32 v[30:31], v[30:31], v[246:247]
	v_rcp_f32_e32 v30, v30
	v_rcp_f32_e32 v31, v31
	s_nop 0
	v_pk_mul_f32 v[22:23], v[22:23], v[30:31]
	s_nop 0
	v_pk_mul_f32 v[22:23], v[18:19], v[22:23]
	v_pk_mul_f32 v[18:19], v[24:25], v[34:35] op_sel_hi:[1,0]
	v_add_u32_e32 v30, 0xa0, v149
	v_pk_mul_f32 v[24:25], v[18:19], v[244:245]
	v_exp_f32_e32 v24, v24
	v_exp_f32_e32 v25, v25
	s_nop 0
	v_pk_add_f32 v[24:25], v[24:25], v[246:247]
	v_rcp_f32_e32 v24, v24
	v_rcp_f32_e32 v25, v25
	s_nop 0
	v_pk_mul_f32 v[18:19], v[18:19], v[24:25]
	s_nop 0
	v_pk_mul_f32 v[24:25], v[20:21], v[18:19]
	v_cvt_pk_bf16_f32 v20, v22, v23
	v_mad_i64_i32 v[22:23], s[30:31], v30, s15, v[114:115]
	v_cvt_pk_bf16_f32 v18, v26, v27
	v_cvt_pk_bf16_f32 v19, v28, v29
	v_cvt_pk_bf16_f32 v21, v24, v25
	v_lshl_add_u64 v[22:23], v[22:23], 0, v[116:117]
	global_store_dwordx4 v[22:23], v[18:21], off sc0 sc1
	s_nop 1
	v_mov_b32_e32 v18, v35
	v_pk_mul_f32 v[14:15], v[14:15], v[18:19] op_sel_hi:[1,0]
	s_nop 0
	v_mul_f32_e32 v19, 0xbfb8aa3b, v14
	v_exp_f32_e32 v19, v19
	s_nop 0
	v_add_f32_e32 v19, 1.0, v19
	v_rcp_f32_e32 v20, v19
	v_pk_mul_f32 v[10:11], v[10:11], v[18:19] op_sel_hi:[1,0]
	v_mul_f32_e32 v19, 0xbfb8aa3b, v15
	v_exp_f32_e32 v19, v19
	s_nop 0
	v_add_f32_e32 v19, 1.0, v19
	v_rcp_f32_e32 v21, v19
	v_pk_mul_f32 v[12:13], v[12:13], v[18:19] op_sel_hi:[1,0]
	v_pk_mul_f32 v[6:7], v[6:7], v[18:19] op_sel_hi:[1,0]
	v_pk_mul_f32 v[2:3], v[2:3], v[18:19] op_sel_hi:[1,0]
	v_pk_mul_f32 v[14:15], v[14:15], v[20:21]
	v_pk_mul_f32 v[4:5], v[4:5], v[18:19] op_sel_hi:[1,0]
	v_pk_mul_f32 v[10:11], v[10:11], v[14:15]
	v_pk_mul_f32 v[14:15], v[16:17], v[18:19] op_sel_hi:[1,0]
	s_nop 0
	v_pk_mul_f32 v[16:17], v[14:15], v[244:245]
	v_exp_f32_e32 v16, v16
	v_exp_f32_e32 v17, v17
	s_nop 0
	v_pk_add_f32 v[16:17], v[16:17], v[246:247]
	v_rcp_f32_e32 v16, v16
	v_rcp_f32_e32 v17, v17
	s_nop 0
	v_pk_mul_f32 v[14:15], v[14:15], v[16:17]
	s_nop 0
	v_pk_mul_f32 v[12:13], v[12:13], v[14:15]
	v_pk_mul_f32 v[14:15], v[6:7], v[244:245]
	v_exp_f32_e32 v14, v14
	v_exp_f32_e32 v15, v15
	s_nop 0
	v_pk_add_f32 v[14:15], v[14:15], v[246:247]
	v_rcp_f32_e32 v14, v14
	v_rcp_f32_e32 v15, v15
	s_nop 0
	v_pk_mul_f32 v[6:7], v[6:7], v[14:15]
	s_nop 0
	v_pk_mul_f32 v[6:7], v[2:3], v[6:7]
	v_pk_mul_f32 v[2:3], v[8:9], v[18:19] op_sel_hi:[1,0]
	v_add_u32_e32 v14, 0xb0, v149
	v_pk_mul_f32 v[8:9], v[2:3], v[244:245]
	v_exp_f32_e32 v8, v8
	v_exp_f32_e32 v9, v9
	s_nop 0
	v_pk_add_f32 v[8:9], v[8:9], v[246:247]
	v_rcp_f32_e32 v8, v8
	v_rcp_f32_e32 v9, v9
	s_nop 0
	v_pk_mul_f32 v[2:3], v[2:3], v[8:9]
	s_nop 0
	v_pk_mul_f32 v[8:9], v[4:5], v[2:3]
	v_cvt_pk_bf16_f32 v4, v6, v7
	v_mad_i64_i32 v[6:7], s[30:31], v14, s15, v[114:115]
	v_cvt_pk_bf16_f32 v2, v10, v11
	v_cvt_pk_bf16_f32 v3, v12, v13
	v_cvt_pk_bf16_f32 v5, v8, v9
	v_lshl_add_u64 v[6:7], v[6:7], 0, v[116:117]
	s_mov_b64 s[30:31], -1
	global_store_dwordx4 v[6:7], v[2:5], off sc0 sc1
	s_cbranch_vccnz .LBB0_808
	s_andn2_b64 vcc, exec, s[8:9]
	s_cbranch_vccnz .LBB0_807
	s_barrier
	s_branch .LBB0_807
